# EpiOut: second residual batch (lower 128 rows) shadow-prefetched into dead operand VGPRs together with the first batch, copied by v_mov at its original site (one exposed load round trip per output til
# baseline (speedup 1.0000x reference)
.LBB0_476:
	v_lshl_or_b32 v174, s86, 8, v199
	v_lshl_add_u32 v176, s87, 8, v196
	v_ashrrev_i32_e32 v175, 31, v174
	v_lshlrev_b64 v[210:211], 1, v[174:175]
	v_ashrrev_i32_e32 v177, 31, v176
	v_or_b32_e32 v188, 16, v176
	v_lshl_add_u64 v[178:179], s[48:49], 0, v[210:211]
	v_lshlrev_b64 v[212:213], 12, v[176:177]
	v_ashrrev_i32_e32 v189, 31, v188
	v_or_b32_e32 v184, 32, v176
	v_lshl_add_u64 v[130:131], v[178:179], 0, v[212:213]
	v_lshlrev_b64 v[190:191], 12, v[188:189]
	v_ashrrev_i32_e32 v185, 31, v184
	v_or_b32_e32 v180, 48, v176
	global_load_dwordx4 v[202:205], v[130:131], off
	global_load_dwordx4 v[206:209], v[130:131], off offset:256
	v_lshl_add_u64 v[130:131], v[178:179], 0, v[190:191]
	v_lshlrev_b64 v[186:187], 12, v[184:185]
	v_ashrrev_i32_e32 v181, 31, v180
	global_load_dwordx4 v[150:153], v[130:131], off
	global_load_dwordx4 v[146:149], v[130:131], off offset:256
	v_lshl_add_u64 v[130:131], v[178:179], 0, v[186:187]
	v_lshlrev_b64 v[182:183], 12, v[180:181]
	global_load_dwordx4 v[142:145], v[130:131], off
	global_load_dwordx4 v[138:141], v[130:131], off offset:256
	v_lshl_add_u64 v[130:131], v[178:179], 0, v[182:183]
	global_load_dwordx4 v[134:137], v[130:131], off
	s_nop 0
	global_load_dwordx4 v[130:133], v[130:131], off offset:256
	s_movk_i32 s100, 0x1000
	v_add_u32_e32 v226, 0x80, v176
	v_mad_u64_u32 v[224:225], s[98:99], v226, s100, v[178:179]
	global_load_dwordx4 v[228:231], v[224:225], off offset:256
	global_load_dwordx4 v[224:227], v[224:225], off
	v_add_u32_e32 v234, 0x90, v176
	v_mad_u64_u32 v[232:233], s[98:99], v234, s100, v[178:179]
	global_load_dwordx4 v[236:239], v[232:233], off offset:256
	global_load_dwordx4 v[232:235], v[232:233], off
	v_add_u32_e32 v246, 0xa0, v176
	v_mad_u64_u32 v[244:245], s[98:99], v246, s100, v[178:179]
	global_load_dwordx4 v[248:251], v[244:245], off offset:256
	global_load_dwordx4 v[244:247], v[244:245], off
	v_add_u32_e32 v254, 0xb0, v176
	v_mad_u64_u32 v[252:253], s[98:99], v254, s100, v[178:179]
	global_load_dwordx4 v[252:255], v[252:253], off
	s_waitcnt vmcnt(7)
	v_lshlrev_b32_e32 v201, 16, v202
	v_and_b32_e32 v202, 0xffff0000, v202
	v_lshlrev_b32_e32 v214, 16, v203
	v_and_b32_e32 v203, 0xffff0000, v203
	v_add_f32_e32 v202, v127, v202
	v_add_f32_e32 v203, v129, v203
	v_add_f32_e32 v201, v126, v201
	v_add_f32_e32 v214, v128, v214
	v_lshlrev_b32_e32 v215, 16, v204
	v_and_b32_e32 v204, 0xffff0000, v204
	v_mul_f32_e32 v217, v202, v202
	v_mul_f32_e32 v218, v203, v203
	v_add_f32_e32 v204, v123, v204
	v_fmac_f32_e32 v217, v201, v201
	v_fmac_f32_e32 v218, v214, v214
	v_add_f32_e32 v215, v122, v215
	v_lshlrev_b32_e32 v216, 16, v205
	v_and_b32_e32 v205, 0xffff0000, v205
	v_add_f32_e32 v217, v217, v218
	v_mul_f32_e32 v218, v204, v204
	v_cvt_pk_bf16_f32 v202, v201, v202
	v_lshlrev_b32_e32 v201, 16, v206
	v_add_f32_e32 v205, v125, v205
	v_fmac_f32_e32 v218, v215, v215
	v_cvt_pk_bf16_f32 v203, v214, v203
	v_add_f32_e32 v214, v94, v201
	v_and_b32_e32 v201, 0xffff0000, v206
	v_add_f32_e32 v216, v124, v216
	v_add_f32_e32 v217, v218, v217
	v_mul_f32_e32 v218, v205, v205
	v_cvt_pk_bf16_f32 v204, v215, v204
	v_add_f32_e32 v215, v95, v201
	v_lshlrev_b32_e32 v201, 16, v207
	v_fmac_f32_e32 v218, v216, v216
	v_cvt_pk_bf16_f32 v205, v216, v205
	v_add_f32_e32 v216, v96, v201
	v_and_b32_e32 v201, 0xffff0000, v207
	v_add_f32_e32 v217, v218, v217
	v_add_f32_e32 v218, v97, v201
	v_lshlrev_b32_e32 v201, 16, v208
	v_add_f32_e32 v219, v90, v201
	v_and_b32_e32 v201, 0xffff0000, v208
	v_add_f32_e32 v208, v91, v201
	v_lshlrev_b32_e32 v201, 16, v209
	v_add_f32_e32 v220, v92, v201
	v_and_b32_e32 v201, 0xffff0000, v209
	v_add_f32_e32 v209, v93, v201
	v_mul_f32_e32 v201, v215, v215
	v_mul_f32_e32 v206, v218, v218
	v_fmac_f32_e32 v201, v214, v214
	v_fmac_f32_e32 v206, v216, v216
	v_add_f32_e32 v201, v201, v206
	v_mul_f32_e32 v206, v208, v208
	v_fmac_f32_e32 v206, v219, v219
	v_add_f32_e32 v201, v206, v201
	v_mul_f32_e32 v206, v209, v209
	v_fmac_f32_e32 v206, v220, v220
	v_add_f32_e32 v201, v206, v201
	v_and_b32_e32 v206, 64, v198
	v_add_f32_e32 v217, v217, v201
	v_xor_b32_e32 v201, 16, v198
	v_add_u32_e32 v221, 64, v206
	v_cmp_lt_i32_e32 vcc, v201, v221
	v_lshl_add_u64 v[206:207], s[50:51], 0, v[212:213]
	v_lshl_add_u64 v[210:211], v[206:207], 0, v[210:211]
	v_cndmask_b32_e32 v201, v198, v201, vcc
	v_lshlrev_b32_e32 v201, 2, v201
	ds_bpermute_b32 v222, v201, v217
	global_store_dwordx4 v[210:211], v[202:205], off
	v_cvt_pk_bf16_f32 v206, v214, v215
	v_cvt_pk_bf16_f32 v207, v216, v218
	v_cvt_pk_bf16_f32 v208, v219, v208
	v_cvt_pk_bf16_f32 v209, v220, v209
	global_store_dwordx4 v[210:211], v[206:209], off offset:256
	s_nop 0
	v_xor_b32_e32 v202, 32, v198
	v_cmp_lt_i32_e32 vcc, v202, v221
	s_waitcnt lgkmcnt(0)
	v_add_f32_e32 v203, v217, v222
	v_cndmask_b32_e32 v202, v198, v202, vcc
	v_lshlrev_b32_e32 v202, 2, v202
	ds_bpermute_b32 v204, v202, v203
	s_and_saveexec_b64 s[10:11], s[38:39]
	s_cbranch_execz .LBB0_478
	v_lshl_add_u64 v[206:207], v[176:177], 2, s[12:13]
	s_waitcnt lgkmcnt(0)
	v_add_f32_e32 v177, v203, v204
	global_atomic_add_f32 v[206:207], v177, off

.LBB0_484:
	s_or_b64 exec, exec, s[10:11]
	v_add_u32_e32 v190, 0x80, v176
	v_ashrrev_i32_e32 v191, 31, v190
	v_add_u32_e32 v186, 0x90, v176
	v_lshlrev_b64 v[212:213], 12, v[190:191]
	v_ashrrev_i32_e32 v187, 31, v186
	v_add_u32_e32 v182, 0xa0, v176
	s_waitcnt lgkmcnt(0)
	v_lshl_add_u64 v[130:131], v[178:179], 0, v[212:213]
	v_lshlrev_b64 v[188:189], 12, v[186:187]
	v_ashrrev_i32_e32 v183, 31, v182
	v_add_u32_e32 v176, 0xb0, v176
	s_nop 0
	s_nop 0
	v_lshl_add_u64 v[130:131], v[178:179], 0, v[188:189]
	v_lshlrev_b64 v[184:185], 12, v[182:183]
	v_ashrrev_i32_e32 v177, 31, v176
	s_nop 0
	s_nop 0
	v_lshl_add_u64 v[130:131], v[178:179], 0, v[184:185]
	v_lshlrev_b64 v[180:181], 12, v[176:177]
	s_nop 0
	s_nop 0
	v_lshl_add_u64 v[130:131], v[178:179], 0, v[180:181]
	s_waitcnt vmcnt(8)
	v_mov_b64_e32 v[204:205], v[224:225]
	v_mov_b64_e32 v[206:207], v[226:227]
	v_mov_b64_e32 v[208:209], v[228:229]
	v_mov_b64_e32 v[210:211], v[230:231]
	v_mov_b64_e32 v[150:151], v[232:233]
	v_mov_b64_e32 v[152:153], v[234:235]
	v_mov_b64_e32 v[146:147], v[236:237]
	v_mov_b64_e32 v[148:149], v[238:239]
	v_mov_b64_e32 v[142:143], v[244:245]
	v_mov_b64_e32 v[144:145], v[246:247]
	v_mov_b64_e32 v[138:139], v[248:249]
	v_mov_b64_e32 v[140:141], v[250:251]
	v_mov_b64_e32 v[134:135], v[252:253]
	v_mov_b64_e32 v[136:137], v[254:255]
	s_nop 0
	global_load_dwordx4 v[130:133], v[130:131], off offset:256
	s_waitcnt vmcnt(7)
	v_lshlrev_b32_e32 v178, 16, v204
	v_and_b32_e32 v179, 0xffff0000, v204
	v_and_b32_e32 v204, 0xffff0000, v205
	v_lshlrev_b32_e32 v203, 16, v205
	v_add_f32_e32 v205, v65, v204
	v_lshlrev_b32_e32 v204, 16, v206
	v_add_f32_e32 v214, v58, v204
	v_and_b32_e32 v204, 0xffff0000, v206
	v_add_f32_e32 v206, v59, v204
	v_lshlrev_b32_e32 v204, 16, v207
	v_add_f32_e32 v179, v63, v179
	v_add_f32_e32 v215, v60, v204
	v_and_b32_e32 v204, 0xffff0000, v207
	v_add_f32_e32 v178, v62, v178
	v_add_f32_e32 v203, v64, v203
	v_add_f32_e32 v207, v61, v204
	v_mul_f32_e32 v204, v179, v179
	v_mul_f32_e32 v216, v205, v205
	v_fmac_f32_e32 v204, v178, v178
	v_fmac_f32_e32 v216, v203, v203
	v_add_f32_e32 v204, v204, v216
	v_mul_f32_e32 v216, v206, v206
	v_fmac_f32_e32 v216, v214, v214
	v_add_f32_e32 v204, v216, v204
	v_mul_f32_e32 v216, v207, v207
	v_fmac_f32_e32 v216, v215, v215
	v_add_f32_e32 v216, v216, v204
	v_cvt_pk_bf16_f32 v204, v178, v179
	s_waitcnt vmcnt(6)
	v_lshlrev_b32_e32 v178, 16, v208
	v_cvt_pk_bf16_f32 v205, v203, v205
	v_add_f32_e32 v203, v30, v178
	v_and_b32_e32 v178, 0xffff0000, v208
	v_cvt_pk_bf16_f32 v206, v214, v206
	v_add_f32_e32 v214, v31, v178
	v_lshlrev_b32_e32 v178, 16, v209
	v_cvt_pk_bf16_f32 v207, v215, v207
	v_add_f32_e32 v215, v32, v178
	v_and_b32_e32 v178, 0xffff0000, v209
	v_add_f32_e32 v217, v33, v178
	v_lshlrev_b32_e32 v178, 16, v210
	v_add_f32_e32 v218, v26, v178
	v_and_b32_e32 v178, 0xffff0000, v210
	v_add_f32_e32 v210, v27, v178
	v_lshlrev_b32_e32 v178, 16, v211
	v_add_f32_e32 v219, v28, v178
	v_and_b32_e32 v178, 0xffff0000, v211
	v_add_f32_e32 v211, v29, v178
	v_mul_f32_e32 v178, v214, v214
	v_mul_f32_e32 v179, v217, v217
	v_fmac_f32_e32 v178, v203, v203
	v_fmac_f32_e32 v179, v215, v215
	v_add_f32_e32 v178, v178, v179
	v_mul_f32_e32 v179, v210, v210
	v_fmac_f32_e32 v179, v218, v218
	v_add_f32_e32 v178, v179, v178
	v_mul_f32_e32 v179, v211, v211
	v_fmac_f32_e32 v179, v219, v219
	v_add_f32_e32 v178, v179, v178
	v_add_f32_e32 v216, v216, v178
	ds_bpermute_b32 v220, v201, v216
	v_lshl_add_u64 v[178:179], s[50:51], 0, v[212:213]
	v_lshl_add_u64 v[208:209], v[174:175], 1, v[178:179]
	global_store_dwordx4 v[208:209], v[204:207], off
	s_waitcnt lgkmcnt(0)
	v_add_f32_e32 v178, v216, v220
	ds_bpermute_b32 v179, v202, v178
	v_cvt_pk_bf16_f32 v204, v203, v214
	v_cvt_pk_bf16_f32 v205, v215, v217
	v_cvt_pk_bf16_f32 v206, v218, v210
	v_cvt_pk_bf16_f32 v207, v219, v211
	global_store_dwordx4 v[208:209], v[204:207], off offset:256
	s_and_saveexec_b64 s[10:11], s[38:39]
	s_cbranch_execz .LBB0_486
	v_lshl_add_u64 v[190:191], v[190:191], 2, s[12:13]
	s_waitcnt lgkmcnt(0)
	v_add_f32_e32 v178, v178, v179
	global_atomic_add_f32 v[190:191], v178, off

.LBB0_869:
	v_lshl_or_b32 v170, s54, 8, v190
	v_lshl_add_u32 v172, s55, 8, v188
	v_ashrrev_i32_e32 v171, 31, v170
	v_lshlrev_b64 v[208:209], 1, v[170:171]
	v_ashrrev_i32_e32 v173, 31, v172
	v_or_b32_e32 v184, 16, v172
	v_lshl_add_u64 v[174:175], s[22:23], 0, v[208:209]
	v_lshlrev_b64 v[210:211], 12, v[172:173]
	v_ashrrev_i32_e32 v185, 31, v184
	v_or_b32_e32 v180, 32, v172
	v_lshl_add_u64 v[132:133], v[174:175], 0, v[210:211]
	v_lshlrev_b64 v[186:187], 12, v[184:185]
	v_ashrrev_i32_e32 v181, 31, v180
	v_or_b32_e32 v176, 48, v172
	global_load_dwordx4 v[192:195], v[132:133], off
	global_load_dwordx4 v[204:207], v[132:133], off offset:256
	v_lshl_add_u64 v[132:133], v[174:175], 0, v[186:187]
	v_lshlrev_b64 v[182:183], 12, v[180:181]
	v_ashrrev_i32_e32 v177, 31, v176
	global_load_dwordx4 v[152:155], v[132:133], off
	global_load_dwordx4 v[148:151], v[132:133], off offset:256
	v_lshl_add_u64 v[132:133], v[174:175], 0, v[182:183]
	v_lshlrev_b64 v[178:179], 12, v[176:177]
	global_load_dwordx4 v[144:147], v[132:133], off
	global_load_dwordx4 v[140:143], v[132:133], off offset:256
	v_lshl_add_u64 v[132:133], v[174:175], 0, v[178:179]
	global_load_dwordx4 v[136:139], v[132:133], off
	s_nop 0
	global_load_dwordx4 v[132:135], v[132:133], off offset:256
	s_movk_i32 s100, 0x1000
	v_add_u32_e32 v226, 0x80, v172
	v_mad_u64_u32 v[224:225], s[98:99], v226, s100, v[174:175]
	global_load_dwordx4 v[228:231], v[224:225], off offset:256
	global_load_dwordx4 v[224:227], v[224:225], off
	v_add_u32_e32 v234, 0x90, v172
	v_mad_u64_u32 v[232:233], s[98:99], v234, s100, v[174:175]
	global_load_dwordx4 v[236:239], v[232:233], off offset:256
	global_load_dwordx4 v[232:235], v[232:233], off
	v_add_u32_e32 v246, 0xa0, v172
	v_mad_u64_u32 v[244:245], s[98:99], v246, s100, v[174:175]
	global_load_dwordx4 v[248:251], v[244:245], off offset:256
	global_load_dwordx4 v[244:247], v[244:245], off
	v_add_u32_e32 v254, 0xb0, v172
	v_mad_u64_u32 v[252:253], s[98:99], v254, s100, v[174:175]
	global_load_dwordx4 v[252:255], v[252:253], off
	s_waitcnt vmcnt(7)
	v_lshlrev_b32_e32 v212, 16, v194
	v_and_b32_e32 v194, 0xffff0000, v194
	v_lshlrev_b32_e32 v196, 16, v192
	v_and_b32_e32 v192, 0xffff0000, v192
	v_lshlrev_b32_e32 v197, 16, v193
	v_and_b32_e32 v193, 0xffff0000, v193
	v_add_f32_e32 v213, v125, v194
	v_lshlrev_b32_e32 v194, 16, v195
	v_add_f32_e32 v192, v129, v192
	v_add_f32_e32 v193, v131, v193
	v_add_f32_e32 v214, v126, v194
	v_and_b32_e32 v194, 0xffff0000, v195
	v_add_f32_e32 v196, v128, v196
	v_add_f32_e32 v197, v130, v197
	v_add_f32_e32 v215, v127, v194
	v_mul_f32_e32 v194, v192, v192
	v_mul_f32_e32 v195, v193, v193
	v_fmac_f32_e32 v194, v196, v196
	v_fmac_f32_e32 v195, v197, v197
	v_add_f32_e32 v212, v124, v212
	v_add_f32_e32 v194, v194, v195
	v_mul_f32_e32 v195, v213, v213
	v_fmac_f32_e32 v195, v212, v212
	v_add_f32_e32 v194, v195, v194
	v_mul_f32_e32 v195, v215, v215
	v_fmac_f32_e32 v195, v214, v214
	v_add_f32_e32 v216, v195, v194
	v_cvt_pk_bf16_f32 v194, v196, v192
	v_lshlrev_b32_e32 v192, 16, v204
	v_cvt_pk_bf16_f32 v195, v197, v193
	v_add_f32_e32 v193, v96, v192
	v_and_b32_e32 v192, 0xffff0000, v204
	v_cvt_pk_bf16_f32 v196, v212, v213
	v_add_f32_e32 v212, v97, v192
	v_lshlrev_b32_e32 v192, 16, v205
	v_add_f32_e32 v213, v98, v192
	v_and_b32_e32 v192, 0xffff0000, v205
	v_cvt_pk_bf16_f32 v197, v214, v215
	v_add_f32_e32 v214, v99, v192
	v_lshlrev_b32_e32 v192, 16, v206
	v_add_f32_e32 v215, v92, v192
	v_and_b32_e32 v192, 0xffff0000, v206
	v_add_f32_e32 v206, v93, v192
	v_lshlrev_b32_e32 v192, 16, v207
	v_add_f32_e32 v217, v94, v192
	v_and_b32_e32 v192, 0xffff0000, v207
	v_add_f32_e32 v207, v95, v192
	v_mul_f32_e32 v192, v212, v212
	v_mul_f32_e32 v204, v214, v214
	v_fmac_f32_e32 v192, v193, v193
	v_fmac_f32_e32 v204, v213, v213
	v_add_f32_e32 v192, v192, v204
	v_mul_f32_e32 v204, v206, v206
	v_fmac_f32_e32 v204, v215, v215
	v_add_f32_e32 v192, v204, v192
	v_mul_f32_e32 v204, v207, v207
	v_fmac_f32_e32 v204, v217, v217
	v_add_f32_e32 v192, v204, v192
	v_and_b32_e32 v204, 64, v198
	v_add_f32_e32 v216, v216, v192
	v_xor_b32_e32 v192, 16, v198
	v_add_u32_e32 v218, 64, v204
	v_cmp_lt_i32_e32 vcc, v192, v218
	v_lshl_add_u64 v[204:205], s[22:23], 0, v[210:211]
	v_lshl_add_u64 v[208:209], v[204:205], 0, v[208:209]
	v_cndmask_b32_e32 v192, v198, v192, vcc
	v_lshlrev_b32_e32 v192, 2, v192
	ds_bpermute_b32 v219, v192, v216
	global_store_dwordx4 v[208:209], v[194:197], off
	v_cvt_pk_bf16_f32 v204, v193, v212
	v_xor_b32_e32 v193, 32, v198
	v_cmp_lt_i32_e32 vcc, v193, v218
	s_waitcnt lgkmcnt(0)
	v_add_f32_e32 v194, v216, v219
	v_cvt_pk_bf16_f32 v205, v213, v214
	v_cvt_pk_bf16_f32 v206, v215, v206
	v_cvt_pk_bf16_f32 v207, v217, v207
	global_store_dwordx4 v[208:209], v[204:207], off offset:256
	v_cndmask_b32_e32 v193, v198, v193, vcc
	v_lshlrev_b32_e32 v193, 2, v193
	ds_bpermute_b32 v195, v193, v194
	s_and_saveexec_b64 s[10:11], s[38:39]
	s_cbranch_execz .LBB0_871
	v_lshl_add_u64 v[196:197], v[172:173], 2, s[8:9]
	s_waitcnt lgkmcnt(0)
	v_add_f32_e32 v173, v194, v195
	global_atomic_add_f32 v[196:197], v173, off

.LBB0_877:
	s_or_b64 exec, exec, s[10:11]
	v_add_u32_e32 v186, 0x80, v172
	v_ashrrev_i32_e32 v187, 31, v186
	v_add_u32_e32 v182, 0x90, v172
	v_lshlrev_b64 v[208:209], 12, v[186:187]
	v_ashrrev_i32_e32 v183, 31, v182
	v_add_u32_e32 v178, 0xa0, v172
	s_waitcnt lgkmcnt(0)
	v_lshl_add_u64 v[132:133], v[174:175], 0, v[208:209]
	v_lshlrev_b64 v[184:185], 12, v[182:183]
	v_ashrrev_i32_e32 v179, 31, v178
	v_add_u32_e32 v172, 0xb0, v172
	s_nop 0
	s_nop 0
	v_lshl_add_u64 v[132:133], v[174:175], 0, v[184:185]
	v_lshlrev_b64 v[180:181], 12, v[178:179]
	v_ashrrev_i32_e32 v173, 31, v172
	s_nop 0
	s_nop 0
	v_lshl_add_u64 v[132:133], v[174:175], 0, v[180:181]
	v_lshlrev_b64 v[176:177], 12, v[172:173]
	s_nop 0
	s_nop 0
	v_lshl_add_u64 v[132:133], v[174:175], 0, v[176:177]
	s_waitcnt vmcnt(8)
	v_mov_b64_e32 v[194:195], v[224:225]
	v_mov_b64_e32 v[196:197], v[226:227]
	v_mov_b64_e32 v[204:205], v[228:229]
	v_mov_b64_e32 v[206:207], v[230:231]
	v_mov_b64_e32 v[152:153], v[232:233]
	v_mov_b64_e32 v[154:155], v[234:235]
	v_mov_b64_e32 v[148:149], v[236:237]
	v_mov_b64_e32 v[150:151], v[238:239]
	v_mov_b64_e32 v[144:145], v[244:245]
	v_mov_b64_e32 v[146:147], v[246:247]
	v_mov_b64_e32 v[140:141], v[248:249]
	v_mov_b64_e32 v[142:143], v[250:251]
	v_mov_b64_e32 v[136:137], v[252:253]
	v_mov_b64_e32 v[138:139], v[254:255]
	s_nop 0
	global_load_dwordx4 v[132:135], v[132:133], off offset:256
	s_waitcnt vmcnt(7)
	v_lshlrev_b32_e32 v174, 16, v194
	v_and_b32_e32 v175, 0xffff0000, v194
	v_lshlrev_b32_e32 v194, 16, v195
	v_add_f32_e32 v210, v66, v194
	v_and_b32_e32 v194, 0xffff0000, v195
	v_add_f32_e32 v195, v67, v194
	v_lshlrev_b32_e32 v194, 16, v196
	v_add_f32_e32 v211, v60, v194
	v_and_b32_e32 v194, 0xffff0000, v196
	v_add_f32_e32 v196, v61, v194
	v_lshlrev_b32_e32 v194, 16, v197
	v_add_f32_e32 v175, v65, v175
	v_add_f32_e32 v212, v62, v194
	v_and_b32_e32 v194, 0xffff0000, v197
	v_add_f32_e32 v174, v64, v174
	v_add_f32_e32 v197, v63, v194
	v_mul_f32_e32 v194, v175, v175
	v_mul_f32_e32 v213, v195, v195
	v_fmac_f32_e32 v194, v174, v174
	v_fmac_f32_e32 v213, v210, v210
	v_add_f32_e32 v194, v194, v213
	v_mul_f32_e32 v213, v196, v196
	v_fmac_f32_e32 v213, v211, v211
	v_add_f32_e32 v194, v213, v194
	v_mul_f32_e32 v213, v197, v197
	v_fmac_f32_e32 v213, v212, v212
	v_add_f32_e32 v213, v213, v194
	v_cvt_pk_bf16_f32 v194, v174, v175
	s_waitcnt vmcnt(6)
	v_lshlrev_b32_e32 v174, 16, v204
	v_cvt_pk_bf16_f32 v195, v210, v195
	v_add_f32_e32 v210, v32, v174
	v_and_b32_e32 v174, 0xffff0000, v204
	v_cvt_pk_bf16_f32 v196, v211, v196
	v_add_f32_e32 v211, v33, v174
	v_lshlrev_b32_e32 v174, 16, v205
	v_cvt_pk_bf16_f32 v197, v212, v197
	v_add_f32_e32 v212, v34, v174
	v_and_b32_e32 v174, 0xffff0000, v205
	v_add_f32_e32 v214, v35, v174
	v_lshlrev_b32_e32 v174, 16, v206
	v_add_f32_e32 v215, v28, v174
	v_and_b32_e32 v174, 0xffff0000, v206
	v_add_f32_e32 v206, v29, v174
	v_lshlrev_b32_e32 v174, 16, v207
	v_add_f32_e32 v216, v30, v174
	v_and_b32_e32 v174, 0xffff0000, v207
	v_add_f32_e32 v207, v31, v174
	v_mul_f32_e32 v174, v211, v211
	v_mul_f32_e32 v175, v214, v214
	v_fmac_f32_e32 v174, v210, v210
	v_fmac_f32_e32 v175, v212, v212
	v_add_f32_e32 v174, v174, v175
	v_mul_f32_e32 v175, v206, v206
	v_fmac_f32_e32 v175, v215, v215
	v_add_f32_e32 v174, v175, v174
	v_mul_f32_e32 v175, v207, v207
	v_fmac_f32_e32 v175, v216, v216
	v_add_f32_e32 v174, v175, v174
	v_add_f32_e32 v213, v213, v174
	ds_bpermute_b32 v217, v192, v213
	v_lshl_add_u64 v[174:175], s[22:23], 0, v[208:209]
	v_lshl_add_u64 v[204:205], v[170:171], 1, v[174:175]
	global_store_dwordx4 v[204:205], v[194:197], off
	s_waitcnt lgkmcnt(0)
	v_add_f32_e32 v174, v213, v217
	ds_bpermute_b32 v175, v193, v174
	v_cvt_pk_bf16_f32 v194, v210, v211
	v_cvt_pk_bf16_f32 v195, v212, v214
	v_cvt_pk_bf16_f32 v196, v215, v206
	v_cvt_pk_bf16_f32 v197, v216, v207
	global_store_dwordx4 v[204:205], v[194:197], off offset:256
	s_and_saveexec_b64 s[10:11], s[38:39]
	s_cbranch_execz .LBB0_879
	v_lshl_add_u64 v[186:187], v[186:187], 2, s[8:9]
	s_waitcnt lgkmcnt(0)
	v_add_f32_e32 v174, v174, v175
	global_atomic_add_f32 v[186:187], v174, off

	.amdhsa_kernel _Z4mega6Params
		.amdhsa_group_segment_fixed_size 0
		.amdhsa_private_segment_fixed_size 0
		.amdhsa_kernarg_size 384
		.amdhsa_user_sgpr_count 2
		.amdhsa_user_sgpr_dispatch_ptr 0
		.amdhsa_user_sgpr_queue_ptr 0
		.amdhsa_user_sgpr_kernarg_segment_ptr 1
		.amdhsa_user_sgpr_dispatch_id 0
		.amdhsa_user_sgpr_kernarg_preload_length 0
		.amdhsa_user_sgpr_kernarg_preload_offset 0
		.amdhsa_user_sgpr_private_segment_size 0
		.amdhsa_uses_dynamic_stack 0
		.amdhsa_enable_private_segment 0
		.amdhsa_system_sgpr_workgroup_id_x 1
		.amdhsa_system_sgpr_workgroup_id_y 0
		.amdhsa_system_sgpr_workgroup_id_z 0
		.amdhsa_system_sgpr_workgroup_info 0
		.amdhsa_system_vgpr_workitem_id 2
		.amdhsa_next_free_vgpr 256
		.amdhsa_next_free_sgpr 102
		.amdhsa_accum_offset 256
		.amdhsa_reserve_vcc 1
		.amdhsa_float_round_mode_32 0
		.amdhsa_float_round_mode_16_64 0
		.amdhsa_float_denorm_mode_32 3
		.amdhsa_float_denorm_mode_16_64 3
		.amdhsa_dx10_clamp 1
		.amdhsa_ieee_mode 1
		.amdhsa_fp16_overflow 0
		.amdhsa_tg_split 0
		.amdhsa_exception_fp_ieee_invalid_op 0
		.amdhsa_exception_fp_denorm_src 0
		.amdhsa_exception_fp_ieee_div_zero 0
		.amdhsa_exception_fp_ieee_overflow 0
		.amdhsa_exception_fp_ieee_underflow 0
		.amdhsa_exception_fp_ieee_inexact 0
		.amdhsa_exception_int_div_zero 0
	.end_amdhsa_kernel

amdhsa.kernels:
  - .agpr_count:     0
    .args:
      - .offset:         0
        .size:           128
        .value_kind:     by_value
      - .offset:         128
        .size:           4
        .value_kind:     hidden_block_count_x
      - .offset:         132
        .size:           4
        .value_kind:     hidden_block_count_y
      - .offset:         136
        .size:           4
        .value_kind:     hidden_block_count_z
      - .offset:         140
        .size:           2
        .value_kind:     hidden_group_size_x
      - .offset:         142
        .size:           2
        .value_kind:     hidden_group_size_y
      - .offset:         144
        .size:           2
        .value_kind:     hidden_group_size_z
      - .offset:         146
        .size:           2
        .value_kind:     hidden_remainder_x
      - .offset:         148
        .size:           2
        .value_kind:     hidden_remainder_y
      - .offset:         150
        .size:           2
        .value_kind:     hidden_remainder_z
      - .offset:         168
        .size:           8
        .value_kind:     hidden_global_offset_x
      - .offset:         176
        .size:           8
        .value_kind:     hidden_global_offset_y
      - .offset:         184
        .size:           8
        .value_kind:     hidden_global_offset_z
      - .offset:         192
        .size:           2
        .value_kind:     hidden_grid_dims
      - .offset:         216
        .size:           8
        .value_kind:     hidden_multigrid_sync_arg
      - .offset:         248
        .size:           4
        .value_kind:     hidden_dynamic_lds_size
    .group_segment_fixed_size: 0
    .kernarg_segment_align: 8
    .kernarg_segment_size: 384
    .language:       OpenCL C
    .language_version:
      - 2
      - 0
    .max_flat_workgroup_size: 512
    .name:           _Z4mega6Params
    .private_segment_fixed_size: 0
    .sgpr_count:     108
    .sgpr_spill_count: 146
    .symbol:         _Z4mega6Params.kd
    .uniform_work_group_size: 1
    .uses_dynamic_stack: false
    .vgpr_count:     256
    .vgpr_spill_count: 0
    .wavefront_size: 64
